# last 912 weight-conversion items (tail of W_gate/up, all of W_down) converted by the 38 idle workgroups at the end of P1 instead of in P0
# speedup vs baseline: 1.0077x; 1.0028x over previous
_Z8skel_fwd4Args:
	s_load_dword s88, s[0:1], 0x118
	s_add_u32 s4, s0, 0x118
	s_addc_u32 s5, s1, 0
	s_mov_b32 s3, 0
	v_writelane_b32 v255, s3, 13
	v_readfirstlane_b32 s94, v0
	v_writelane_b32 v254, s4, 0
	s_waitcnt lgkmcnt(0)
	s_and_b32 s3, s88, 7
	s_cmp_lg_u32 s3, 0
	s_mov_b32 s90, s2
	v_writelane_b32 v254, s5, 1
	s_cbranch_scc1 .LBB0_2
	s_ashr_i32 s4, s2, 31
	s_lshr_b32 s4, s4, 29
	s_add_i32 s4, s2, s4
	s_and_b32 s5, s4, -8
	s_ashr_i32 s3, s88, 3
	s_sub_i32 s5, s2, s5
	s_mul_i32 s3, s3, s5
	s_ashr_i32 s4, s4, 3
	s_add_i32 s90, s3, s4

.LBB0_7:
	s_or_b64 exec, exec, s[4:5]
	s_load_dwordx16 s[4:19], s[0:1], 0x0
	s_load_dwordx16 s[36:51], s[0:1], 0xc0
	s_lshr_b32 s33, s94, 6
	s_add_u32 s96, s86, 0x4500000
	s_addc_u32 s97, s87, 0
	s_waitcnt lgkmcnt(0)
	v_writelane_b32 v254, s4, 9
	v_and_b32_e32 v174, 63, v0
	s_nop 0
	v_writelane_b32 v254, s5, 10
	v_writelane_b32 v254, s6, 11
	v_writelane_b32 v254, s7, 12
	v_writelane_b32 v254, s8, 13
	v_writelane_b32 v254, s9, 14
	v_writelane_b32 v254, s10, 15
	v_writelane_b32 v254, s11, 16
	v_writelane_b32 v254, s12, 17
	v_writelane_b32 v254, s13, 18
	v_writelane_b32 v254, s14, 19
	v_writelane_b32 v254, s15, 20
	v_writelane_b32 v254, s16, 21
	v_writelane_b32 v254, s17, 22
	v_writelane_b32 v254, s18, 23
	v_writelane_b32 v254, s19, 24
	v_writelane_b32 v254, s36, 25
	s_load_dwordx16 s[68:83], s[0:1], 0x40
	s_load_dwordx2 s[92:93], s[0:1], 0x110
	s_load_dwordx16 s[16:31], s[0:1], 0x80
	v_writelane_b32 v254, s37, 26
	v_writelane_b32 v254, s38, 27
	v_writelane_b32 v254, s39, 28
	v_writelane_b32 v254, s40, 29
	v_writelane_b32 v254, s41, 30
	v_writelane_b32 v254, s42, 31
	v_writelane_b32 v254, s43, 32
	v_writelane_b32 v254, s44, 33
	v_writelane_b32 v254, s45, 34
	s_waitcnt lgkmcnt(0)
	s_cmp_lt_i32 s92, 1
	v_writelane_b32 v254, s46, 35
	s_cselect_b64 s[4:5], -1, 0
	s_cmp_gt_i32 s93, 0
	v_writelane_b32 v254, s47, 36
	s_cselect_b64 s[6:7], -1, 0
	v_writelane_b32 v254, s48, 37
	v_writelane_b32 v254, s49, 38
	s_and_b64 s[0:1], s[4:5], s[6:7]
	v_writelane_b32 v254, s50, 39
	s_andn2_b64 vcc, exec, s[0:1]
	v_writelane_b32 v254, s51, 40
	s_cbranch_vccnz .LBB0_355
	s_movk_i32 s99, 0x17ef
	s_lshl_b32 s0, s90, 3
	s_add_i32 s89, s0, s33
	s_lshl_b32 s91, s88, 3
.Lp0_items_entry:
	s_cmp_gt_i32 s89, s99
	s_cbranch_scc1 .LBB0_275
	v_lshlrev_b32_e32 v2, 3, v0
	s_lshl_b32 s0, s33, 14
	v_lshrrev_b32_e32 v96, 3, v174
	v_and_b32_e32 v2, 56, v2
	s_add_i32 s3, s0, 0
	v_mul_u32_u24_e32 v4, 0x84, v2
	v_lshlrev_b32_e32 v5, 1, v96
	v_readlane_b32 s36, v254, 25
	v_add3_u32 v97, s3, v4, v5
	v_and_b32_e32 v4, 15, v0
	v_readlane_b32 s45, v254, 34
	v_readlane_b32 s47, v254, 36
	v_readlane_b32 s44, v254, 33
	v_readlane_b32 s46, v254, 35
	v_mov_b32_e32 v5, s45
	v_mov_b32_e32 v7, s47
	v_cmp_lt_u32_e32 vcc, 7, v4
	v_mov_b32_e32 v4, s44
	v_lshlrev_b32_e32 v68, 1, v2
	v_cndmask_b32_e32 v5, v5, v7, vcc
	v_mov_b32_e32 v7, s46
	v_mov_b32_e32 v69, 0
	v_cndmask_b32_e32 v4, v4, v7, vcc
	v_and_b32_e32 v7, 7, v0
	v_lshl_add_u64 v[2:3], s[86:87], 0, v[68:69]
	v_lshlrev_b32_e32 v68, 4, v7
	v_lshl_add_u64 v[72:73], v[4:5], 0, v[68:69]
	v_lshrrev_b32_e32 v4, 2, v0
	v_and_b32_e32 v4, 2, v4
	v_lshrrev_b32_e32 v66, 4, v174
	s_movk_i32 s4, 0x84
	v_add3_u32 v105, s3, v68, v4
	v_mov_b32_e32 v4, 0x210
	s_mov_b64 s[0:1], 0x3f00000
	v_mad_u32_u24 v106, v66, s4, v4
	v_mov_b32_e32 v4, 0x420
	v_lshl_add_u64 v[70:71], v[2:3], 0, s[0:1]
	v_mad_u32_u24 v107, v66, s4, v4
	v_mov_b32_e32 v4, 0x630
	s_mov_b64 s[0:1], 0x3400000
	v_readlane_b32 s42, v254, 31
	v_readlane_b32 s43, v254, 32
	v_mad_u32_u24 v108, v66, s4, v4
	v_mov_b32_e32 v4, 0x840
	v_lshl_add_u64 v[74:75], v[2:3], 0, s[0:1]
	s_mov_b64 s[0:1], 0x3200000
	s_cmp_lg_u64 s[42:43], 0
	v_mad_u32_u24 v109, v66, s4, v4
	v_mov_b32_e32 v4, 0xa50
	v_lshl_add_u64 v[76:77], v[2:3], 0, s[0:1]
	s_mov_b64 s[0:1], 0x3000000
	s_cselect_b64 s[64:65], -1, 0
	v_mad_u32_u24 v110, v66, s4, v4
	v_mov_b32_e32 v4, 0xc60
	s_cmp_lg_u64 s[26:27], 0
	v_lshl_add_u64 v[78:79], v[2:3], 0, s[0:1]
	s_mov_b64 s[0:1], 0x2e00000
	v_mad_u32_u24 v111, v66, s4, v4
	v_mov_b32_e32 v4, 0xe70
	s_cselect_b64 s[66:67], -1, 0
	v_lshl_add_u64 v[80:81], v[2:3], 0, s[0:1]
	s_cmp_lg_u64 s[20:21], 0
	s_mov_b64 s[0:1], 0x2c00000
	v_mad_u32_u24 v112, v66, s4, v4
	v_mov_b32_e32 v4, 0x1080
	s_cselect_b64 s[8:9], -1, 0
	v_lshl_add_u64 v[82:83], v[2:3], 0, s[0:1]
	s_cmp_lg_u64 s[82:83], 0
	s_mov_b64 s[0:1], 0x2800000
	v_lshlrev_b32_e32 v1, 2, v0
	v_mad_u32_u24 v113, v66, s4, v4
	v_mov_b32_e32 v4, 0x1290
	s_cselect_b64 s[10:11], -1, 0
	v_lshl_add_u64 v[84:85], v[2:3], 0, s[0:1]
	s_cmp_lg_u64 s[28:29], 0
	s_mov_b64 s[0:1], 0x2400000
	v_and_b32_e32 v1, 60, v1
	v_mad_u32_u24 v114, v66, s4, v4
	v_mov_b32_e32 v4, 0x14a0
	s_cselect_b64 s[12:13], -1, 0
	v_lshl_add_u64 v[86:87], v[2:3], 0, s[0:1]
	s_cmp_lg_u64 s[68:69], 0
	s_mov_b64 s[0:1], 0xd00000
	v_lshl_add_u32 v94, v1, 1, s3
	v_mad_u32_u24 v115, v66, s4, v4
	v_mov_b32_e32 v4, 0x16b0
	s_cselect_b64 s[44:45], -1, 0
	v_lshl_add_u64 v[88:89], v[2:3], 0, s[0:1]
	s_lshl_b32 s0, s89, 2
	v_mul_u32_u24_e32 v6, 0x84, v66
	v_mad_u32_u24 v95, v66, s4, v94
	v_readlane_b32 s37, v254, 26
	v_readlane_b32 s38, v254, 27
	v_readlane_b32 s39, v254, 28
	v_readlane_b32 s40, v254, 29
	v_readlane_b32 s41, v254, 30
	v_mad_u32_u24 v116, v66, s4, v4
	v_mov_b32_e32 v4, 0x18c0
	s_add_i32 s36, s0, 0x39d00
	s_lshl_b32 s0, s89, 1
	v_or_b32_e32 v98, 8, v96
	v_or_b32_e32 v99, 16, v96
	v_or_b32_e32 v100, 24, v96
	v_or_b32_e32 v101, 32, v96
	v_or_b32_e32 v102, 40, v96
	v_or_b32_e32 v103, 48, v96
	v_or_b32_e32 v104, 56, v96
	s_movk_i32 s95, 0x420
	s_movk_i32 s6, 0x630
	v_mad_u32_u24 v117, v66, s4, v4
	v_mov_b32_e32 v67, v69
	s_lshl_b32 s7, s89, 6
	s_lshl_b32 s3, s91, 6
	s_lshl_b32 s37, s91, 2
	s_add_i32 s38, s0, 0x1e980
	s_lshl_b32 s39, s91, 1
	v_add_u32_e32 v118, 0x420, v95
	v_add_u32_e32 v119, 0x630, v95
	v_add_u32_e32 v120, 0x840, v95
	v_add_u32_e32 v121, v105, v6
	v_add_u32_e32 v122, 0xa50, v95
	v_add_u32_e32 v123, 0xc60, v95
	v_add_u32_e32 v124, 0xe70, v95
	s_mov_b32 s40, 0x2c000
	s_mov_b32 s41, 0xb080
	s_mov_b32 s42, s89
	s_mov_b32 s47, 0
	v_readlane_b32 s48, v254, 37
	v_readlane_b32 s49, v254, 38
	v_readlane_b32 s50, v254, 39
	v_readlane_b32 s51, v254, 40
	s_branch .LBB0_12

.LBB0_11:
	s_add_i32 s42, s42, s91
	s_add_i32 s7, s7, s3
	s_add_i32 s36, s36, s37
	s_add_i32 s38, s38, s39
	s_cmp_gt_i32 s42, s99
	s_cbranch_scc1 .LBB0_275

.LBB0_275:
	v_readlane_b32 s0, v255, 13
	s_nop 0
	s_cmp_eq_u32 s0, 1
	s_cbranch_scc1 .Lp1t_ret
	s_cmpk_gt_i32 s89, 0x107f
	v_lshlrev_b32_e32 v50, 2, v174
	v_cmp_eq_u32_e64 s[4:5], 0, v174
	s_cbranch_scc1 .LBB0_290
	v_mbcnt_lo_u32_b32 v1, -1, 0
	v_mbcnt_hi_u32_b32 v3, -1, v1
	v_and_b32_e32 v1, 64, v3
	v_add_u32_e32 v5, 64, v1
	v_xor_b32_e32 v1, 1, v3
	v_cmp_lt_i32_e32 vcc, v1, v5
	v_xor_b32_e32 v7, 2, v3
	s_add_u32 s3, s86, 0x100000
	v_cndmask_b32_e32 v1, v3, v1, vcc
	v_cmp_lt_i32_e32 vcc, v7, v5
	s_addc_u32 s14, s87, 0
	v_mov_b32_e32 v53, 0
	v_cndmask_b32_e32 v7, v3, v7, vcc
	v_lshlrev_b32_e32 v51, 2, v7
	v_xor_b32_e32 v7, 4, v3
	v_cmp_lt_i32_e32 vcc, v7, v5
	v_or_b32_e32 v2, 0x100, v50
	v_or_b32_e32 v4, 0x200, v50
	v_cndmask_b32_e32 v7, v3, v7, vcc
	v_lshlrev_b32_e32 v58, 2, v7
	v_xor_b32_e32 v7, 8, v3
	v_cmp_lt_i32_e32 vcc, v7, v5
	v_or_b32_e32 v6, 0x300, v50
	v_lshlrev_b32_e32 v52, 3, v174
	v_cndmask_b32_e32 v7, v3, v7, vcc
	v_lshlrev_b32_e32 v59, 2, v7
	v_xor_b32_e32 v7, 16, v3
	v_cmp_lt_i32_e32 vcc, v7, v5
	s_lshl_b32 s0, s90, 5
	s_lshl_b32 s1, s33, 2
	v_cndmask_b32_e32 v7, v3, v7, vcc
	v_lshlrev_b32_e32 v60, 2, v7
	v_xor_b32_e32 v7, 32, v3
	v_cmp_lt_i32_e32 vcc, v7, v5
	s_mov_b32 s7, 0
	v_lshlrev_b32_e32 v1, 2, v1
	v_cndmask_b32_e32 v3, v3, v7, vcc
	v_lshlrev_b32_e32 v61, 2, v3
	v_lshl_add_u64 v[54:55], s[96:97], 0, v[52:53]
	s_add_i32 s8, s0, s1
	s_lshl_b32 s15, s88, 5
	v_lshlrev_b32_e32 v52, 2, v50
	v_lshlrev_b32_e32 v62, 2, v2
	v_lshlrev_b32_e32 v63, 2, v4
	v_lshlrev_b32_e32 v64, 2, v6
	v_mov_b32_e32 v65, 0x358637bd
	s_mov_b32 s16, 0xf800000
	v_mov_b32_e32 v66, 0x260
	s_movk_i32 s17, 0x1000
	s_mov_b32 s20, s89
	s_branch .LBB0_278

.LBB0_540:
	s_sub_u32 s0, s2, 0x9a
	s_cmp_lt_u32 s0, 38
	s_cbranch_scc0 .Lp1t_skip
	s_barrier
	v_writelane_b32 v255, s10, 20
	v_writelane_b32 v255, s12, 21
	v_writelane_b32 v255, s15, 22
	v_writelane_b32 v255, s16, 23
	v_writelane_b32 v255, s17, 24
	v_writelane_b32 v255, s18, 25
	v_writelane_b32 v255, s19, 26
	v_writelane_b32 v255, s20, 27
	v_writelane_b32 v255, s21, 28
	v_writelane_b32 v255, s22, 29
	v_writelane_b32 v255, s23, 30
	v_writelane_b32 v255, s24, 31
	v_writelane_b32 v255, s25, 32
	v_writelane_b32 v255, s26, 33
	v_writelane_b32 v255, s27, 34
	v_writelane_b32 v255, s28, 35
	v_writelane_b32 v255, s29, 36
	v_writelane_b32 v255, s30, 37
	v_writelane_b32 v255, s31, 38
	v_writelane_b32 v255, s34, 39
	v_writelane_b32 v255, s46, 40
	v_writelane_b32 v255, s47, 41
	v_writelane_b32 v255, s48, 42
	v_writelane_b32 v255, s91, 43
	v_mov_b32_e32 v200, v3
	v_mov_b32_e32 v201, v4
	v_mov_b32_e32 v202, v5
	v_mov_b32_e32 v203, v25
	v_mov_b32_e32 v204, v26
	v_mov_b32_e32 v205, v27
	v_mov_b32_e32 v206, v45
	v_mov_b32_e32 v207, v46
	v_mov_b32_e32 v208, v64
	v_mov_b32_e32 v209, v65
	v_mov_b32_e32 v210, v66
	v_mov_b32_e32 v211, v67
	v_mov_b32_e32 v212, v123
	s_mov_b64 s[100:101], exec
	v_readlane_b32 s4, v254, 0
	v_readlane_b32 s5, v254, 1
	s_nop 1
	s_sub_u32 s4, s4, 0x118
	s_subb_u32 s5, s5, 0
	s_load_dwordx16 s[16:31], s[4:5], 0x80
	s_lshl_b32 s0, s0, 3
	s_add_i32 s89, s0, s33
	s_addk_i32 s89, 0x17f0
	s_movk_i32 s91, 0x130
	s_movk_i32 s99, 0x1b7f
	s_mov_b32 s1, 1
	v_writelane_b32 v255, s1, 13
	s_waitcnt lgkmcnt(0)
	s_branch .Lp0_items_entry
.Lp1t_ret:
	s_mov_b32 s0, 0
	v_writelane_b32 v255, s0, 13
	s_waitcnt vmcnt(0) lgkmcnt(0)
	s_mov_b64 exec, s[100:101]
	v_mov_b32_e32 v3, v200
	v_mov_b32_e32 v4, v201
	v_mov_b32_e32 v5, v202
	v_mov_b32_e32 v25, v203
	v_mov_b32_e32 v26, v204
	v_mov_b32_e32 v27, v205
	v_mov_b32_e32 v45, v206
	v_mov_b32_e32 v46, v207
	v_mov_b32_e32 v64, v208
	v_mov_b32_e32 v65, v209
	v_mov_b32_e32 v66, v210
	v_mov_b32_e32 v67, v211
	v_mov_b32_e32 v123, v212
	v_readlane_b32 s10, v255, 20
	v_readlane_b32 s12, v255, 21
	v_readlane_b32 s15, v255, 22
	v_readlane_b32 s16, v255, 23
	v_readlane_b32 s17, v255, 24
	v_readlane_b32 s18, v255, 25
	v_readlane_b32 s19, v255, 26
	v_readlane_b32 s20, v255, 27
	v_readlane_b32 s21, v255, 28
	v_readlane_b32 s22, v255, 29
	v_readlane_b32 s23, v255, 30
	v_readlane_b32 s24, v255, 31
	v_readlane_b32 s25, v255, 32
	v_readlane_b32 s26, v255, 33
	v_readlane_b32 s27, v255, 34
	v_readlane_b32 s28, v255, 35
	v_readlane_b32 s29, v255, 36
	v_readlane_b32 s30, v255, 37
	v_readlane_b32 s31, v255, 38
	v_readlane_b32 s34, v255, 39
	v_readlane_b32 s46, v255, 40
	v_readlane_b32 s47, v255, 41
	v_readlane_b32 s48, v255, 42
	v_readlane_b32 s91, v255, 43
	s_nop 3
